# swa units: output gates, sink and rope rows requested at the top of the unit (were issued late and waited for)
# speedup vs baseline: 1.0006x; 1.0006x over previous
.LBB0_640:
	s_waitcnt lgkmcnt(0)
	s_barrier
	ds_read_b128 v[2:5], v49
	ds_read_b128 v[70:73], v49 offset:64
	ds_read_b128 v[6:9], v49 offset:18432
	ds_read_b128 v[10:13], v49 offset:18496
	ds_read_b128 v[74:77], v67 offset:18496
	s_waitcnt lgkmcnt(2)
	v_mfma_f32_16x16x32_bf16 v[6:9], v[6:9], v[2:5], 0
	s_mov_b32 s11, s1
	v_readlane_b32 s36, v249, 16
	s_lshl_b64 s[12:13], s[10:11], 2
	s_waitcnt lgkmcnt(1)
	v_mfma_f32_16x16x32_bf16 v[38:41], v[10:13], v[70:73], v[6:9]
	ds_read_b128 v[10:13], v60 offset:18496
	v_readlane_b32 s38, v249, 18
	s_nop 0
	ds_read_b128 v[6:9], v60 offset:18432
	v_readlane_b32 s39, v249, 19
	s_waitcnt lgkmcnt(0)
	v_mfma_f32_16x16x32_bf16 v[6:9], v[6:9], v[2:5], 0
	s_add_u32 s12, s38, s12
	s_addc_u32 s13, s39, s13
	s_nop 0
	v_mfma_f32_16x16x32_bf16 v[34:37], v[10:13], v[70:73], v[6:9]
	ds_read_b128 v[10:13], v61 offset:18496
	v_readlane_b32 s12, v249, 57
	v_readlane_b32 s13, v249, 58
	s_nop 0
	ds_read_b128 v[6:9], v61 offset:18432
	s_waitcnt lgkmcnt(0)
	v_mfma_f32_16x16x32_bf16 v[6:9], v[6:9], v[2:5], 0
	v_cndmask_b32_e64 v38, v69, v38, s[12:13]
	v_readlane_b32 s12, v249, 59
	v_readlane_b32 s13, v249, 60
	v_mfma_f32_16x16x32_bf16 v[30:33], v[10:13], v[70:73], v[6:9]
	ds_read_b128 v[10:13], v62 offset:18496
	v_cndmask_b32_e64 v39, v69, v39, s[12:13]
	v_readlane_b32 s12, v249, 61
	s_nop 0
	ds_read_b128 v[6:9], v62 offset:18432
	s_waitcnt lgkmcnt(0)
	v_mfma_f32_16x16x32_bf16 v[6:9], v[6:9], v[2:5], 0
	v_readlane_b32 s13, v249, 62
	s_movk_i32 s11, 0x3000
	s_add_i32 s15, s15, 1
	v_mfma_f32_16x16x32_bf16 v[26:29], v[10:13], v[70:73], v[6:9]
	ds_read_b128 v[10:13], v63 offset:18496
	v_cndmask_b32_e64 v40, v69, v40, s[12:13]
	v_readlane_b32 s12, v249, 63
	s_nop 0
	ds_read_b128 v[6:9], v63 offset:18432
	s_waitcnt lgkmcnt(0)
	v_mfma_f32_16x16x32_bf16 v[6:9], v[6:9], v[2:5], 0
	v_readlane_b32 s13, v248, 0
	s_addk_i32 s14, 0x100
	v_readlane_b32 s37, v249, 17
	v_mfma_f32_16x16x32_bf16 v[22:25], v[10:13], v[70:73], v[6:9]
	ds_read_b128 v[10:13], v64 offset:18496
	v_cndmask_b32_e64 v41, v69, v41, s[12:13]
	v_readlane_b32 s12, v248, 1
	s_nop 0
	ds_read_b128 v[6:9], v64 offset:18432
	s_waitcnt lgkmcnt(0)
	v_mfma_f32_16x16x32_bf16 v[6:9], v[6:9], v[2:5], 0
	v_readlane_b32 s13, v248, 2
	v_cndmask_b32_e64 v22, v69, v22, s[30:31]
	v_cndmask_b32_e64 v23, v69, v23, s[34:35]
	v_mfma_f32_16x16x32_bf16 v[18:21], v[10:13], v[70:73], v[6:9]
	ds_read_b128 v[10:13], v65 offset:18496
	v_cndmask_b32_e64 v34, v69, v34, s[12:13]
	v_readlane_b32 s12, v248, 3
	s_nop 0
	ds_read_b128 v[6:9], v65 offset:18432
	s_waitcnt lgkmcnt(0)
	v_mfma_f32_16x16x32_bf16 v[6:9], v[6:9], v[2:5], 0
	v_readlane_b32 s13, v248, 4
	s_waitcnt vmcnt(0)
	v_mov_b32_e32 v44, v114
	v_max3_f32 v47, v44, v38, v39
	v_max3_f32 v47, v47, v40, v41
	v_mfma_f32_16x16x32_bf16 v[14:17], v[10:13], v[70:73], v[6:9]
	ds_read_b128 v[10:13], v66 offset:18496
	v_cndmask_b32_e64 v35, v69, v35, s[12:13]
	v_readlane_b32 s12, v248, 5
	ds_read_b128 v[6:9], v66 offset:18432
	s_waitcnt lgkmcnt(0)
	v_mfma_f32_16x16x32_bf16 v[6:9], v[6:9], v[2:5], 0
	v_readlane_b32 s13, v248, 6
	v_max3_f32 v47, v47, v34, v35
	v_cndmask_b32_e64 v24, v69, v24, s[20:21]
	v_mfma_f32_16x16x32_bf16 v[10:13], v[10:13], v[70:73], v[6:9]
	v_cndmask_b32_e64 v36, v69, v36, s[12:13]
	v_readlane_b32 s12, v248, 7
	v_readlane_b32 s13, v248, 8
	s_nop 0
	ds_read_b128 v[6:9], v67 offset:18432
	s_waitcnt lgkmcnt(0)
	v_mfma_f32_16x16x32_bf16 v[6:9], v[6:9], v[2:5], 0
	v_cndmask_b32_e64 v37, v69, v37, s[12:13]
	v_readlane_b32 s12, v248, 9
	v_readlane_b32 s13, v248, 10
	v_mfma_f32_16x16x32_bf16 v[6:9], v[74:77], v[70:73], v[6:9]
	ds_read_b128 v[74:77], v68 offset:18432
	v_cndmask_b32_e64 v30, v69, v30, s[12:13]
	v_readlane_b32 s12, v248, 11
	v_readlane_b32 s13, v248, 12
	s_waitcnt lgkmcnt(0)
	v_mfma_f32_16x16x32_bf16 v[2:5], v[74:77], v[2:5], 0
	v_cndmask_b32_e64 v31, v69, v31, s[12:13]
	v_readlane_b32 s12, v248, 13
	v_readlane_b32 s13, v248, 14
	ds_read_b128 v[74:77], v68 offset:18496
	v_max3_f32 v47, v47, v36, v37
	v_cndmask_b32_e64 v32, v69, v32, s[12:13]
	v_readlane_b32 s12, v248, 15
	v_readlane_b32 s13, v248, 16
	v_max3_f32 v47, v47, v30, v31
	v_cndmask_b32_e64 v25, v69, v25, s[24:25]
	v_cndmask_b32_e64 v33, v69, v33, s[12:13]
	v_readlane_b32 s12, v248, 17
	v_readlane_b32 s13, v248, 18
	v_max3_f32 v47, v47, v32, v33
	s_waitcnt lgkmcnt(0)
	v_mfma_f32_16x16x32_bf16 v[2:5], v[74:77], v[70:73], v[2:5]
	v_cndmask_b32_e64 v26, v69, v26, s[12:13]
	v_readlane_b32 s12, v248, 19
	v_readlane_b32 s13, v248, 20
	v_cndmask_b32_e64 v70, v69, v18, s[26:27]
	v_cndmask_b32_e64 v71, v69, v19, s[28:29]
	v_cndmask_b32_e64 v27, v69, v27, s[12:13]
	v_readlane_b32 s12, v248, 21
	v_readlane_b32 s13, v248, 22
	v_max3_f32 v47, v47, v26, v27
	v_cndmask_b32_e64 v72, v69, v21, s[54:55]
	v_cndmask_b32_e64 v28, v69, v28, s[12:13]
	v_readlane_b32 s12, v248, 23
	v_readlane_b32 s13, v248, 24
	v_cndmask_b32_e64 v73, v69, v14, s[56:57]
	v_cndmask_b32_e64 v74, v69, v15, s[58:59]
	v_cndmask_b32_e64 v29, v69, v29, s[12:13]
	v_max3_f32 v47, v47, v28, v29
	v_max3_f32 v47, v47, v22, v23
	v_max3_f32 v47, v47, v24, v25
	v_max3_f32 v18, v47, v70, v71
	v_cndmask_b32_e64 v47, v69, v20, s[52:53]
	v_max3_f32 v18, v18, v47, v72
	v_max3_f32 v14, v18, v73, v74
	v_cndmask_b32_e64 v75, v69, v16, s[60:61]
	v_cndmask_b32_e64 v76, v69, v17, s[62:63]
	v_max3_f32 v14, v14, v75, v76
	v_cndmask_b32_e64 v77, v69, v10, s[64:65]
	v_cndmask_b32_e64 v78, v69, v11, s[66:67]
	v_max3_f32 v10, v14, v77, v78
	v_cndmask_b32_e64 v79, v69, v12, s[68:69]
	v_cndmask_b32_e64 v80, v69, v13, s[70:71]
	v_max3_f32 v10, v10, v79, v80
	v_cndmask_b32_e64 v81, v69, v6, s[72:73]
	v_cndmask_b32_e64 v82, v69, v7, s[74:75]
	v_max3_f32 v6, v10, v81, v82
	v_cndmask_b32_e64 v83, v69, v8, s[76:77]
	v_cndmask_b32_e64 v84, v69, v9, s[78:79]
	v_max3_f32 v6, v6, v83, v84
	v_cndmask_b32_e64 v85, v69, v2, s[80:81]
	v_cndmask_b32_e64 v86, v69, v3, s[82:83]
	v_max3_f32 v2, v6, v85, v86
	v_cndmask_b32_e64 v87, v69, v4, s[84:85]
	v_cndmask_b32_e64 v88, v69, v5, s[86:87]
	v_max3_f32 v2, v2, v87, v88
	ds_bpermute_b32 v3, v1, v2
	v_readlane_b32 s40, v249, 20
	v_readlane_b32 s41, v249, 21
	v_readlane_b32 s42, v249, 22
	v_readlane_b32 s43, v249, 23
	s_waitcnt lgkmcnt(0)
	v_max_f32_e32 v3, v3, v3
	v_max_f32_e32 v2, v2, v3
	ds_bpermute_b32 v3, v43, v2
	v_readlane_b32 s44, v249, 24
	v_readlane_b32 s45, v249, 25
	v_readlane_b32 s46, v249, 26
	v_readlane_b32 s47, v249, 27
	s_waitcnt lgkmcnt(0)
	v_max_f32_e32 v3, v3, v3
	v_max_f32_e32 v89, v2, v3
	v_sub_f32_e32 v2, v38, v89
	v_mul_f32_e32 v2, 0x3fb8aa3b, v2
	v_sub_f32_e32 v3, v39, v89
	v_exp_f32_e32 v2, v2
	v_mul_f32_e32 v3, 0x3fb8aa3b, v3
	v_exp_f32_e32 v3, v3
	v_sub_f32_e32 v44, v44, v89
	v_add_f32_e32 v4, 0, v2
	v_mul_f32_e32 v44, 0x3fb8aa3b, v44
	v_add_f32_e32 v5, v3, v4
	v_sub_f32_e32 v4, v40, v89
	v_mul_f32_e32 v4, 0x3fb8aa3b, v4
	v_exp_f32_e32 v4, v4
	v_exp_f32_e32 v44, v44
	v_readlane_b32 s48, v249, 28
	v_readlane_b32 s49, v249, 29
	v_add_f32_e32 v6, v4, v5
	v_sub_f32_e32 v5, v41, v89
	v_mul_f32_e32 v5, 0x3fb8aa3b, v5
	v_exp_f32_e32 v5, v5
	v_readlane_b32 s50, v249, 30
	v_readlane_b32 s51, v249, 31
	v_add_f32_e32 v7, v5, v6
	v_sub_f32_e32 v6, v34, v89
	v_mul_f32_e32 v6, 0x3fb8aa3b, v6
	v_exp_f32_e32 v6, v6
	s_nop 0
	v_add_f32_e32 v8, v6, v7
	v_sub_f32_e32 v7, v35, v89
	v_mul_f32_e32 v7, 0x3fb8aa3b, v7
	v_exp_f32_e32 v7, v7
	s_nop 0
	v_add_f32_e32 v9, v7, v8
	v_sub_f32_e32 v8, v36, v89
	v_mul_f32_e32 v8, 0x3fb8aa3b, v8
	v_exp_f32_e32 v8, v8
	s_nop 0
	v_add_f32_e32 v10, v8, v9
	v_sub_f32_e32 v9, v37, v89
	v_mul_f32_e32 v9, 0x3fb8aa3b, v9
	v_exp_f32_e32 v9, v9
	s_nop 0
	v_add_f32_e32 v11, v9, v10
	v_sub_f32_e32 v10, v30, v89
	v_mul_f32_e32 v10, 0x3fb8aa3b, v10
	v_exp_f32_e32 v10, v10
	s_nop 0
	v_add_f32_e32 v12, v10, v11
	v_sub_f32_e32 v11, v31, v89
	v_mul_f32_e32 v11, 0x3fb8aa3b, v11
	v_exp_f32_e32 v11, v11
	s_nop 0
	v_add_f32_e32 v13, v11, v12
	v_sub_f32_e32 v12, v32, v89
	v_mul_f32_e32 v12, 0x3fb8aa3b, v12
	v_exp_f32_e32 v12, v12
	s_nop 0
	v_add_f32_e32 v14, v12, v13
	v_sub_f32_e32 v13, v33, v89
	v_mul_f32_e32 v13, 0x3fb8aa3b, v13
	v_exp_f32_e32 v13, v13
	s_nop 0
	v_add_f32_e32 v15, v13, v14
	v_sub_f32_e32 v14, v26, v89
	v_mul_f32_e32 v14, 0x3fb8aa3b, v14
	v_exp_f32_e32 v14, v14
	s_nop 0
	v_add_f32_e32 v16, v14, v15
	v_sub_f32_e32 v15, v27, v89
	v_mul_f32_e32 v15, 0x3fb8aa3b, v15
	v_exp_f32_e32 v15, v15
	s_nop 0
	v_add_f32_e32 v17, v15, v16
	v_sub_f32_e32 v16, v28, v89
	v_mul_f32_e32 v16, 0x3fb8aa3b, v16
	v_exp_f32_e32 v16, v16
	s_nop 0
	v_add_f32_e32 v18, v16, v17
	v_sub_f32_e32 v17, v29, v89
	v_mul_f32_e32 v17, 0x3fb8aa3b, v17
	v_exp_f32_e32 v17, v17
	s_nop 0
	v_add_f32_e32 v19, v17, v18
	v_sub_f32_e32 v18, v22, v89
	v_mul_f32_e32 v18, 0x3fb8aa3b, v18
	v_exp_f32_e32 v18, v18
	s_nop 0
	v_add_f32_e32 v20, v18, v19
	v_sub_f32_e32 v19, v23, v89
	v_mul_f32_e32 v19, 0x3fb8aa3b, v19
	v_exp_f32_e32 v19, v19
	s_nop 0
	v_add_f32_e32 v21, v19, v20
	v_sub_f32_e32 v20, v24, v89
	v_mul_f32_e32 v20, 0x3fb8aa3b, v20
	v_exp_f32_e32 v20, v20
	s_nop 0
	v_add_f32_e32 v22, v20, v21
	v_sub_f32_e32 v21, v25, v89
	v_mul_f32_e32 v21, 0x3fb8aa3b, v21
	v_exp_f32_e32 v21, v21
	s_nop 0
	v_add_f32_e32 v23, v21, v22
	v_sub_f32_e32 v22, v70, v89
	v_mul_f32_e32 v22, 0x3fb8aa3b, v22
	v_exp_f32_e32 v22, v22
	s_nop 0
	v_add_f32_e32 v24, v22, v23
	v_sub_f32_e32 v23, v71, v89
	v_mul_f32_e32 v23, 0x3fb8aa3b, v23
	v_exp_f32_e32 v23, v23
	s_nop 0
	v_add_f32_e32 v25, v23, v24
	v_sub_f32_e32 v24, v47, v89
	v_mul_f32_e32 v24, 0x3fb8aa3b, v24
	v_exp_f32_e32 v24, v24
	s_nop 0
	v_add_f32_e32 v26, v24, v25
	v_sub_f32_e32 v25, v72, v89
	v_mul_f32_e32 v25, 0x3fb8aa3b, v25
	v_exp_f32_e32 v25, v25
	s_nop 0
	v_add_f32_e32 v27, v25, v26
	v_sub_f32_e32 v26, v73, v89
	v_mul_f32_e32 v26, 0x3fb8aa3b, v26
	v_exp_f32_e32 v26, v26
	s_nop 0
	v_add_f32_e32 v28, v26, v27
	v_sub_f32_e32 v27, v74, v89
	v_mul_f32_e32 v27, 0x3fb8aa3b, v27
	v_exp_f32_e32 v27, v27
	s_nop 0
	v_add_f32_e32 v29, v27, v28
	v_sub_f32_e32 v28, v75, v89
	v_mul_f32_e32 v28, 0x3fb8aa3b, v28
	v_exp_f32_e32 v28, v28
	s_nop 0
	v_add_f32_e32 v30, v28, v29
	v_sub_f32_e32 v29, v76, v89
	v_mul_f32_e32 v29, 0x3fb8aa3b, v29
	v_exp_f32_e32 v29, v29
	s_nop 0
	v_add_f32_e32 v31, v29, v30
	v_sub_f32_e32 v30, v77, v89
	v_mul_f32_e32 v30, 0x3fb8aa3b, v30
	v_exp_f32_e32 v30, v30
	s_nop 0
	v_add_f32_e32 v32, v30, v31
	v_sub_f32_e32 v31, v78, v89
	v_mul_f32_e32 v31, 0x3fb8aa3b, v31
	v_exp_f32_e32 v31, v31
	s_nop 0
	v_add_f32_e32 v33, v31, v32
	v_sub_f32_e32 v32, v79, v89
	v_mul_f32_e32 v32, 0x3fb8aa3b, v32
	v_exp_f32_e32 v32, v32
	s_nop 0
	v_add_f32_e32 v34, v32, v33
	v_sub_f32_e32 v33, v80, v89
	v_mul_f32_e32 v33, 0x3fb8aa3b, v33
	v_exp_f32_e32 v33, v33
	s_nop 0
	v_add_f32_e32 v35, v33, v34
	v_sub_f32_e32 v34, v81, v89
	v_mul_f32_e32 v34, 0x3fb8aa3b, v34
	v_exp_f32_e32 v34, v34
	s_nop 0
	v_add_f32_e32 v36, v34, v35
	v_sub_f32_e32 v35, v82, v89
	v_mul_f32_e32 v35, 0x3fb8aa3b, v35
	v_exp_f32_e32 v35, v35
	s_nop 0
	v_add_f32_e32 v37, v35, v36
	v_sub_f32_e32 v36, v83, v89
	v_mul_f32_e32 v36, 0x3fb8aa3b, v36
	v_exp_f32_e32 v36, v36
	s_nop 0
	v_add_f32_e32 v38, v36, v37
	v_sub_f32_e32 v37, v84, v89
	v_mul_f32_e32 v37, 0x3fb8aa3b, v37
	v_exp_f32_e32 v37, v37
	s_nop 0
	v_add_f32_e32 v39, v37, v38
	v_sub_f32_e32 v38, v85, v89
	v_mul_f32_e32 v38, 0x3fb8aa3b, v38
	v_exp_f32_e32 v38, v38
	s_nop 0
	v_add_f32_e32 v40, v38, v39
	v_sub_f32_e32 v39, v86, v89
	v_mul_f32_e32 v39, 0x3fb8aa3b, v39
	v_exp_f32_e32 v39, v39
	s_nop 0
	v_add_f32_e32 v41, v39, v40
	v_sub_f32_e32 v40, v87, v89
	v_mul_f32_e32 v40, 0x3fb8aa3b, v40
	v_exp_f32_e32 v40, v40
	s_nop 0
	v_add_f32_e32 v47, v40, v41
	v_sub_f32_e32 v41, v88, v89
	v_mul_f32_e32 v41, 0x3fb8aa3b, v41
	v_exp_f32_e32 v41, v41
	s_nop 0
	v_add_f32_e32 v47, v41, v47
	ds_bpermute_b32 v70, v1, v47
	s_waitcnt lgkmcnt(0)
	v_add_f32_e32 v47, v47, v70
	ds_bpermute_b32 v70, v43, v47
	s_waitcnt lgkmcnt(0)
	v_add_f32_e32 v47, v47, v70
	v_add_f32_e32 v44, v44, v47
	v_div_scale_f32 v47, s[12:13], v44, v44, 1.0
	v_rcp_f32_e32 v70, v47
	s_nop 0
	v_fma_f32 v71, -v47, v70, 1.0
	v_fmac_f32_e32 v70, v71, v70
	v_div_scale_f32 v71, vcc, 1.0, v44, 1.0
	v_mul_f32_e32 v72, v71, v70
	v_fma_f32 v73, -v47, v72, v71
	v_fmac_f32_e32 v72, v73, v70
	v_fma_f32 v47, -v47, v72, v71
	v_div_fmas_f32 v47, v47, v70, v72
	v_div_fixup_f32 v44, v47, v44, 1.0
	v_pk_mul_f32 v[2:3], v[2:3], v[44:45] op_sel_hi:[1,0]
	v_pk_mul_f32 v[4:5], v[4:5], v[44:45] op_sel_hi:[1,0]
	v_cvt_pk_bf16_f32 v2, v2, v3
	v_cvt_pk_bf16_f32 v3, v4, v5
	v_pk_mul_f32 v[4:5], v[6:7], v[44:45] op_sel_hi:[1,0]
	v_pk_mul_f32 v[6:7], v[8:9], v[44:45] op_sel_hi:[1,0]
	v_cvt_pk_bf16_f32 v4, v4, v5
	v_cvt_pk_bf16_f32 v5, v6, v7
	ds_write2_b64 v50, v[2:3], v[4:5] offset1:4
	v_pk_mul_f32 v[2:3], v[10:11], v[44:45] op_sel_hi:[1,0]
	v_pk_mul_f32 v[4:5], v[12:13], v[44:45] op_sel_hi:[1,0]
	v_cvt_pk_bf16_f32 v2, v2, v3
	v_cvt_pk_bf16_f32 v3, v4, v5
	v_pk_mul_f32 v[4:5], v[14:15], v[44:45] op_sel_hi:[1,0]
	v_pk_mul_f32 v[6:7], v[16:17], v[44:45] op_sel_hi:[1,0]
	v_cvt_pk_bf16_f32 v4, v4, v5
	v_cvt_pk_bf16_f32 v5, v6, v7
	ds_write2_b64 v50, v[2:3], v[4:5] offset0:8 offset1:12
	v_pk_mul_f32 v[2:3], v[18:19], v[44:45] op_sel_hi:[1,0]
	v_pk_mul_f32 v[4:5], v[20:21], v[44:45] op_sel_hi:[1,0]
	v_cvt_pk_bf16_f32 v2, v2, v3
	v_cvt_pk_bf16_f32 v3, v4, v5
	v_pk_mul_f32 v[4:5], v[22:23], v[44:45] op_sel_hi:[1,0]
	v_pk_mul_f32 v[6:7], v[24:25], v[44:45] op_sel_hi:[1,0]
	v_cvt_pk_bf16_f32 v4, v4, v5
	v_cvt_pk_bf16_f32 v5, v6, v7
	ds_write2_b64 v50, v[2:3], v[4:5] offset0:16 offset1:20
	v_pk_mul_f32 v[2:3], v[26:27], v[44:45] op_sel_hi:[1,0]
	v_pk_mul_f32 v[4:5], v[28:29], v[44:45] op_sel_hi:[1,0]
	v_cvt_pk_bf16_f32 v2, v2, v3
	v_cvt_pk_bf16_f32 v3, v4, v5
	v_pk_mul_f32 v[4:5], v[30:31], v[44:45] op_sel_hi:[1,0]
	v_pk_mul_f32 v[6:7], v[32:33], v[44:45] op_sel_hi:[1,0]
	v_cvt_pk_bf16_f32 v4, v4, v5
	v_cvt_pk_bf16_f32 v5, v6, v7
	ds_write2_b64 v50, v[2:3], v[4:5] offset0:24 offset1:28
	v_pk_mul_f32 v[2:3], v[34:35], v[44:45] op_sel_hi:[1,0]
	v_pk_mul_f32 v[4:5], v[36:37], v[44:45] op_sel_hi:[1,0]
	v_cvt_pk_bf16_f32 v2, v2, v3
	v_cvt_pk_bf16_f32 v3, v4, v5
	v_pk_mul_f32 v[4:5], v[38:39], v[44:45] op_sel_hi:[1,0]
	v_pk_mul_f32 v[6:7], v[40:41], v[44:45] op_sel_hi:[1,0]
	v_cvt_pk_bf16_f32 v4, v4, v5
	v_cvt_pk_bf16_f32 v5, v6, v7
	ds_write2_b64 v50, v[2:3], v[4:5] offset0:32 offset1:36
	s_waitcnt lgkmcnt(0)
	ds_read_b128 v[2:5], v52
	ds_read_b64_tr_b16 v[8:9], v53 offset:58176
	ds_read_b64_tr_b16 v[6:7], v53 offset:57600
	ds_read_b64_tr_b16 v[10:11], v53 offset:57632
	ds_read_b64_tr_b16 v[12:13], v53 offset:58208
	ds_read_b64_tr_b16 v[14:15], v53 offset:57664
	ds_read_b64_tr_b16 v[16:17], v53 offset:58240
	ds_read_b64_tr_b16 v[18:19], v53 offset:57696
	ds_read_b64_tr_b16 v[20:21], v53 offset:58272
	s_waitcnt lgkmcnt(6)
	v_mfma_f32_16x16x32_bf16 v[6:9], v[6:9], v[2:5], 0
	v_mov_b32_e32 v47, v45
	s_waitcnt lgkmcnt(4)
	v_mfma_f32_16x16x32_bf16 v[10:13], v[10:13], v[2:5], 0
	s_waitcnt lgkmcnt(2)
	v_mfma_f32_16x16x32_bf16 v[14:17], v[14:17], v[2:5], 0
	s_waitcnt lgkmcnt(0)
	v_mfma_f32_16x16x32_bf16 v[2:5], v[18:21], v[2:5], 0
	ds_read_b128 v[18:21], v52 offset:64
	ds_read_b64_tr_b16 v[22:23], v53 offset:62208
	ds_read_b64_tr_b16 v[24:25], v53 offset:62784
	s_waitcnt lgkmcnt(0)
	v_mfma_f32_16x16x32_bf16 v[6:9], v[22:25], v[18:21], v[6:9]
	ds_read_b64_tr_b16 v[22:23], v53 offset:62240
	ds_read_b64_tr_b16 v[24:25], v53 offset:62816
	s_waitcnt lgkmcnt(0)
	v_mfma_f32_16x16x32_bf16 v[10:13], v[22:25], v[18:21], v[10:13]
	ds_read_b64_tr_b16 v[22:23], v53 offset:62272
	ds_read_b64_tr_b16 v[24:25], v53 offset:62848
	s_waitcnt lgkmcnt(0)
	v_mfma_f32_16x16x32_bf16 v[14:17], v[22:25], v[18:21], v[14:17]
	ds_read_b64_tr_b16 v[22:23], v53 offset:62304
	ds_read_b64_tr_b16 v[24:25], v53 offset:62880
	s_waitcnt lgkmcnt(0)
	v_mfma_f32_16x16x32_bf16 v[2:5], v[22:25], v[18:21], v[2:5]
	ds_read_b128 v[18:21], v52 offset:128
	ds_read_b64_tr_b16 v[24:25], v54 offset:9792
	ds_read_b64_tr_b16 v[22:23], v54 offset:9216
	ds_read_b64_tr_b16 v[26:27], v54 offset:9248
	ds_read_b64_tr_b16 v[28:29], v54 offset:9824
	s_waitcnt lgkmcnt(2)
	v_mfma_f32_16x16x32_bf16 v[6:9], v[22:25], v[18:21], v[6:9]
	ds_read_b64_tr_b16 v[22:23], v54 offset:9280
	ds_read_b64_tr_b16 v[24:25], v54 offset:9856
	s_waitcnt lgkmcnt(0)
	v_mfma_f32_16x16x32_bf16 v[14:17], v[22:25], v[18:21], v[14:17]
	ds_read_b64_tr_b16 v[22:23], v54 offset:9312
	ds_read_b64_tr_b16 v[24:25], v54 offset:9888
	v_mfma_f32_16x16x32_bf16 v[10:13], v[26:29], v[18:21], v[10:13]
	v_add_u32_e32 v28, s16, v48
	v_lshlrev_b32_e32 v29, 6, v28
	v_and_b32_e32 v30, 0x3c0, v29
	s_waitcnt lgkmcnt(0)
	v_mfma_f32_16x16x32_bf16 v[2:5], v[22:25], v[18:21], v[2:5]
	ds_read_b128 v[18:21], v52 offset:192
	ds_read_b64_tr_b16 v[22:23], v54 offset:13824
	ds_read_b64_tr_b16 v[24:25], v54 offset:14400
	s_waitcnt lgkmcnt(0)
	v_mfma_f32_16x16x32_bf16 v[6:9], v[22:25], v[18:21], v[6:9]
	ds_read_b64_tr_b16 v[22:23], v54 offset:13856
	ds_read_b64_tr_b16 v[24:25], v54 offset:14432
	s_waitcnt lgkmcnt(0)
	v_mfma_f32_16x16x32_bf16 v[10:13], v[22:25], v[18:21], v[10:13]
	ds_read_b64_tr_b16 v[22:23], v54 offset:13888
	ds_read_b64_tr_b16 v[24:25], v54 offset:14464
	s_waitcnt lgkmcnt(0)
	v_mfma_f32_16x16x32_bf16 v[22:25], v[22:25], v[18:21], v[14:17]
	s_nop 2
	ds_read_b64_tr_b16 v[14:15], v54 offset:13920
	ds_read_b64_tr_b16 v[16:17], v54 offset:14496
	s_waitcnt lgkmcnt(0)
	v_mfma_f32_16x16x32_bf16 v[2:5], v[14:17], v[18:21], v[2:5]
	ds_read_b128 v[18:21], v52 offset:256
	ds_read_b64_tr_b16 v[14:15], v54 offset:18432
	ds_read_b64_tr_b16 v[16:17], v54 offset:19008
	s_waitcnt lgkmcnt(0)
	v_mfma_f32_16x16x32_bf16 v[14:17], v[14:17], v[18:21], v[6:9]
	s_nop 2
	ds_read_b64_tr_b16 v[6:7], v54 offset:18464
	ds_read_b64_tr_b16 v[8:9], v54 offset:19040
	s_waitcnt lgkmcnt(0)
	v_mfma_f32_16x16x32_bf16 v[10:13], v[6:9], v[18:21], v[10:13]
	ds_read_b64_tr_b16 v[6:7], v54 offset:18496
	ds_read_b64_tr_b16 v[8:9], v54 offset:19072
	s_waitcnt lgkmcnt(0)
	v_mfma_f32_16x16x32_bf16 v[6:9], v[6:9], v[18:21], v[22:25]
	s_nop 2
	ds_read_b64_tr_b16 v[22:23], v54 offset:18528
	ds_read_b64_tr_b16 v[24:25], v54 offset:19104
	s_waitcnt lgkmcnt(0)
	v_mfma_f32_16x16x32_bf16 v[2:5], v[22:25], v[18:21], v[2:5]
	v_mov_b64_e32 v[18:19], s[2:3]
	v_mad_i64_i32 v[18:19], s[12:13], v28, s33, v[18:19]
	s_lshl_b32 s12, s10, 7
	s_mov_b32 s13, s1
	v_lshl_add_u64 v[18:19], v[18:19], 0, s[12:13]
	v_lshl_add_u64 v[18:19], v[18:19], 0, v[46:47]
	s_mov_b64 s[12:13], 0x3200
	v_lshl_add_u64 v[24:25], v[18:19], 0, s[12:13]
	v_add_co_u32_e32 v18, vcc, s11, v18
	s_add_i32 s10, s10, 32
	s_nop 0
	v_addc_co_u32_e32 v19, vcc, 0, v19, vcc
	v_mov_b32_e32 v26, v106
	v_mov_b32_e32 v27, v107
	v_mov_b32_e32 v22, v108
	v_mov_b32_e32 v23, v109
	v_mov_b32_e32 v20, v110
	v_mov_b32_e32 v21, v111
	v_mov_b32_e32 v18, v112
	v_mov_b32_e32 v19, v113
	v_ashrrev_i32_e32 v24, 7, v28
	v_ashrrev_i32_e32 v25, 31, v24
	v_lshlrev_b64 v[24:25], 20, v[24:25]
	v_lshlrev_b32_e32 v28, 2, v28
	s_waitcnt vmcnt(3)
	v_and_b32_e32 v31, 32, v28
	v_lshl_add_u64 v[28:29], s[6:7], 0, v[24:25]
	v_lshlrev_b32_e32 v24, 16, v26
	v_and_b32_e32 v25, 0xffff0000, v26
	v_pk_mul_f32 v[14:15], v[14:15], v[24:25]
	s_mov_b32 s11, s1
	v_cvt_pk_bf16_f32 v24, v14, v15
	v_lshlrev_b32_e32 v14, 16, v27
	v_and_b32_e32 v15, 0xffff0000, v27
	v_pk_mul_f32 v[14:15], v[16:17], v[14:15]
	s_lshl_b64 s[10:11], s[10:11], 14
	v_cvt_pk_bf16_f32 v25, v14, v15
	v_or3_b32 v44, v30, v55, v31
	v_lshl_add_u64 v[14:15], v[28:29], 0, s[10:11]
	s_waitcnt vmcnt(2)
	v_lshl_add_u64 v[16:17], v[14:15], 0, v[44:45]
	s_waitcnt vmcnt(1)
	s_waitcnt vmcnt(0)
	global_store_dwordx2 v[16:17], v[24:25], off
	v_lshlrev_b32_e32 v24, 16, v22
	v_and_b32_e32 v25, 0xffff0000, v22
	v_lshlrev_b32_e32 v22, 16, v23
	v_and_b32_e32 v23, 0xffff0000, v23
	v_pk_mul_f32 v[12:13], v[12:13], v[22:23]
	v_or_b32_e32 v22, v30, v56
	v_pk_mul_f32 v[10:11], v[10:11], v[24:25]
	v_bitop3_b32 v44, v31, s9, v22 bitop3:0xde
	v_cvt_pk_bf16_f32 v10, v10, v11
	v_cvt_pk_bf16_f32 v11, v12, v13
	v_lshl_add_u64 v[12:13], v[14:15], 0, v[44:45]
	global_store_dwordx2 v[12:13], v[10:11], off
	v_lshlrev_b32_e32 v10, 16, v20
	v_and_b32_e32 v11, 0xffff0000, v20
	v_pk_mul_f32 v[6:7], v[6:7], v[10:11]
	v_lshlrev_b32_e32 v10, 16, v21
	v_and_b32_e32 v11, 0xffff0000, v21
	v_pk_mul_f32 v[8:9], v[8:9], v[10:11]
	v_cvt_pk_bf16_f32 v6, v6, v7
	v_cvt_pk_bf16_f32 v7, v8, v9
	global_store_dwordx2 v[16:17], v[6:7], off offset:1024
	v_lshlrev_b32_e32 v6, 16, v18
	v_and_b32_e32 v7, 0xffff0000, v18
	v_pk_mul_f32 v[2:3], v[2:3], v[6:7]
	v_lshlrev_b32_e32 v6, 16, v19
	v_and_b32_e32 v7, 0xffff0000, v19
	v_pk_mul_f32 v[4:5], v[4:5], v[6:7]
	v_xad_u32 v44, v31, v22, s9
	v_cvt_pk_bf16_f32 v2, v2, v3
	v_cvt_pk_bf16_f32 v3, v4, v5
	v_lshl_add_u64 v[4:5], v[14:15], 0, v[44:45]
	s_cmp_eq_u32 s15, 4
	global_store_dwordx2 v[4:5], v[2:3], off offset:1024
	s_cbranch_scc1 .LBB0_652
.LBB0_641:
	s_lshl_b32 s11, s15, 8
	s_add_i32 s11, s11, s17
	s_and_b32 s11, s11, 0xfffff000
	s_or_b32 s10, s23, s15
	s_or_b32 s16, s11, s22
	v_lshlrev_b32_e32 v44, 1, v42
	v_add_u32_e32 v100, s16, v48
	v_mov_b64_e32 v[102:103], s[2:3]
	v_mad_i64_i32 v[102:103], s[12:13], v100, s33, v[102:103]
	s_lshl_b32 s12, s10, 7
	s_mov_b32 s13, s1
	v_lshl_add_u64 v[102:103], v[102:103], 0, s[12:13]
	v_mov_b32_e32 v104, v46
	v_mov_b32_e32 v105, 0
	v_lshl_add_u64 v[102:103], v[102:103], 0, v[104:105]
	s_mov_b64 s[12:13], 0x3200
	v_lshl_add_u64 v[102:103], v[102:103], 0, s[12:13]
	global_load_dwordx2 v[106:107], v[102:103], off
	global_load_dwordx2 v[108:109], v[102:103], off offset:32
	global_load_dwordx2 v[110:111], v[102:103], off offset:64
	global_load_dwordx2 v[112:113], v[102:103], off offset:96
	v_readlane_b32 s12, v249, 18
	v_readlane_b32 s13, v249, 19
	v_lshlrev_b32_e64 v101, 2, s10
	s_nop 4
	global_load_dword v114, v101, s[12:13]
	s_barrier
	s_mov_b64 s[90:91], exec
	v_readlane_b32 s12, v249, 55
	v_readlane_b32 s13, v249, 56
	s_and_b64 s[12:13], s[90:91], s[12:13]
	s_mov_b64 exec, s[12:13]
	s_cbranch_execz .LBB0_645
	v_or_b32_e32 v12, s16, v51
	v_mov_b64_e32 v[2:3], s[2:3]
	v_mad_i64_i32 v[2:3], s[12:13], v12, s33, v[2:3]
	s_lshl_b32 s12, s10, 7
	s_mov_b32 s13, s1
	v_lshl_add_u64 v[2:3], v[2:3], 0, s[12:13]
	v_lshl_add_u64 v[2:3], v[2:3], 0, v[44:45]
	v_add_co_u32_e32 v4, vcc, 0x2000, v2
	s_mov_b64 s[12:13], 0x2800
	s_nop 0
	v_addc_co_u32_e32 v5, vcc, 0, v3, vcc
	v_lshl_add_u64 v[2:3], v[2:3], 0, s[12:13]
	global_load_dwordx4 v[8:11], v[4:5], off offset:2048
	global_load_dwordx4 v[14:17], v[2:3], off offset:16
	s_and_saveexec_b64 s[12:13], s[88:89]
	v_mov_b32_e32 v116, v12
	v_ashrrev_i32_e32 v117, 31, v12
	v_lshlrev_b64 v[116:117], 6, v[116:117]
	v_lshl_add_u64 v[116:117], s[96:97], 0, v[116:117]
	global_load_dwordx4 v[120:123], v[116:117], off offset:48
	global_load_dwordx4 v[124:127], v[116:117], off offset:32
	global_load_dwordx4 v[128:131], v[116:117], off offset:16
	global_load_dwordx4 v[132:135], v[116:117], off
	s_mov_b64 exec, s[12:13]
	s_waitcnt vmcnt(5)
	v_lshlrev_b32_e32 v2, 16, v11
	v_lshlrev_b32_e32 v20, 16, v8
	v_and_b32_e32 v21, 0xffff0000, v8
	s_waitcnt vmcnt(4)
	v_lshlrev_b32_e32 v4, 16, v14
	v_and_b32_e32 v5, 0xffff0000, v14
	v_lshlrev_b32_e32 v24, 16, v9
	v_and_b32_e32 v25, 0xffff0000, v9
	v_lshlrev_b32_e32 v6, 16, v15
	v_and_b32_e32 v7, 0xffff0000, v15
	v_lshlrev_b32_e32 v22, 16, v10
	v_and_b32_e32 v23, 0xffff0000, v10
	v_lshlrev_b32_e32 v8, 16, v16
	v_and_b32_e32 v9, 0xffff0000, v16
	v_lshlrev_b32_e32 v14, 16, v17
	v_and_b32_e32 v11, 0xffff0000, v11
	v_and_b32_e32 v10, 0xffff0000, v17
	s_and_saveexec_b64 s[12:13], s[88:89]
	s_cbranch_execz .LBB0_644
	v_ashrrev_i32_e32 v13, 31, v12
	v_lshlrev_b64 v[12:13], 6, v[12:13]
	v_lshl_add_u64 v[12:13], s[96:97], 0, v[12:13]
	s_waitcnt vmcnt(0)
	v_mov_b32_e32 v26, v120
	v_mov_b32_e32 v27, v121
	v_mov_b32_e32 v28, v122
	v_mov_b32_e32 v29, v123
	v_mov_b32_e32 v30, v124
	v_mov_b32_e32 v31, v125
	v_mov_b32_e32 v32, v126
	v_mov_b32_e32 v33, v127
	v_mov_b32_e32 v16, v128
	v_mov_b32_e32 v17, v129
	v_mov_b32_e32 v18, v130
	v_mov_b32_e32 v19, v131
	v_mov_b32_e32 v34, v132
	v_mov_b32_e32 v35, v133
	v_mov_b32_e32 v36, v134
	v_mov_b32_e32 v37, v135
	v_mov_b32_e32 v3, v11
	v_mov_b32_e32 v15, v10
	s_waitcnt vmcnt(3)
	v_pk_mul_f32 v[10:11], v[28:29], v[10:11]
	s_waitcnt vmcnt(0)
	v_mov_b32_e32 v39, v36
	v_mov_b32_e32 v36, v35
	v_mov_b32_e32 v38, v34
	v_pk_mul_f32 v[12:13], v[36:37], v[4:5]
	s_nop 0
	v_pk_fma_f32 v[12:13], v[38:39], v[20:21], v[12:13] neg_lo:[0,0,1] neg_hi:[0,0,1]
	v_pk_mul_f32 v[20:21], v[36:37], v[20:21]
	s_nop 0
	v_pk_fma_f32 v[4:5], v[38:39], v[4:5], v[20:21]
	v_mov_b32_e32 v21, v18
	v_mov_b32_e32 v18, v17
	v_mov_b32_e32 v20, v16
	v_pk_mul_f32 v[16:17], v[18:19], v[6:7]
	v_pk_mul_f32 v[18:19], v[18:19], v[24:25]
	v_pk_fma_f32 v[16:17], v[20:21], v[24:25], v[16:17] neg_lo:[0,0,1] neg_hi:[0,0,1]
	v_pk_fma_f32 v[6:7], v[20:21], v[6:7], v[18:19]
	v_mov_b32_e32 v21, v32
	v_mov_b32_e32 v32, v31
	v_mov_b32_e32 v20, v30
	v_pk_mul_f32 v[18:19], v[32:33], v[8:9]
	v_mov_b32_e32 v24, v26
	v_pk_fma_f32 v[18:19], v[20:21], v[22:23], v[18:19] neg_lo:[0,0,1] neg_hi:[0,0,1]
	v_pk_mul_f32 v[22:23], v[32:33], v[22:23]
	v_mov_b32_e32 v25, v28
	v_pk_fma_f32 v[8:9], v[20:21], v[8:9], v[22:23]
	v_mul_f32_e32 v20, v26, v14
	v_mul_f32_e32 v22, v27, v2
	v_mov_b32_e32 v26, v27
	v_mov_b32_e32 v27, v29
	v_pk_mul_f32 v[14:15], v[26:27], v[14:15]
	v_mov_b32_e32 v21, v10
	v_mov_b32_e32 v23, v11
	v_pk_fma_f32 v[2:3], v[24:25], v[2:3], v[14:15] neg_lo:[0,0,1] neg_hi:[0,0,1]
	v_pk_add_f32 v[14:15], v[20:21], v[22:23]
	v_mov_b32_e32 v20, v12
	v_mov_b32_e32 v21, v13
	v_mov_b32_e32 v24, v16
	v_mov_b32_e32 v25, v17
	v_mov_b32_e32 v22, v18
	v_mov_b32_e32 v23, v19
	v_mov_b32_e32 v11, v3
	v_mov_b32_e32 v10, v15

.LBB0_1423:
	s_waitcnt lgkmcnt(0)
	s_barrier
	ds_read_b128 v[2:5], v50
	ds_read_b128 v[70:73], v50 offset:64
	ds_read_b128 v[6:9], v50 offset:18432
	ds_read_b128 v[10:13], v50 offset:18496
	ds_read_b128 v[74:77], v67 offset:18496
	s_waitcnt lgkmcnt(2)
	v_mfma_f32_16x16x32_bf16 v[6:9], v[6:9], v[2:5], 0
	s_mov_b32 s11, s3
	v_readlane_b32 s36, v249, 16
	s_lshl_b64 s[12:13], s[10:11], 2
	s_waitcnt lgkmcnt(1)
	v_mfma_f32_16x16x32_bf16 v[38:41], v[10:13], v[70:73], v[6:9]
	ds_read_b128 v[10:13], v60 offset:18496
	v_readlane_b32 s38, v249, 18
	s_nop 0
	ds_read_b128 v[6:9], v60 offset:18432
	v_readlane_b32 s39, v249, 19
	s_waitcnt lgkmcnt(0)
	v_mfma_f32_16x16x32_bf16 v[6:9], v[6:9], v[2:5], 0
	s_add_u32 s12, s38, s12
	s_addc_u32 s13, s39, s13
	s_nop 0
	v_mfma_f32_16x16x32_bf16 v[34:37], v[10:13], v[70:73], v[6:9]
	ds_read_b128 v[10:13], v61 offset:18496
	v_readlane_b32 s12, v249, 55
	v_readlane_b32 s13, v249, 56
	s_nop 0
	ds_read_b128 v[6:9], v61 offset:18432
	s_waitcnt lgkmcnt(0)
	v_mfma_f32_16x16x32_bf16 v[6:9], v[6:9], v[2:5], 0
	v_cndmask_b32_e64 v38, v69, v38, s[12:13]
	v_readlane_b32 s12, v249, 57
	v_readlane_b32 s13, v249, 58
	v_mfma_f32_16x16x32_bf16 v[30:33], v[10:13], v[70:73], v[6:9]
	ds_read_b128 v[10:13], v62 offset:18496
	v_cndmask_b32_e64 v39, v69, v39, s[12:13]
	v_readlane_b32 s12, v249, 59
	s_nop 0
	ds_read_b128 v[6:9], v62 offset:18432
	s_waitcnt lgkmcnt(0)
	v_mfma_f32_16x16x32_bf16 v[6:9], v[6:9], v[2:5], 0
	v_readlane_b32 s13, v249, 60
	s_movk_i32 s11, 0x3000
	s_add_i32 s15, s15, 1
	v_mfma_f32_16x16x32_bf16 v[26:29], v[10:13], v[70:73], v[6:9]
	ds_read_b128 v[10:13], v63 offset:18496
	v_cndmask_b32_e64 v40, v69, v40, s[12:13]
	v_readlane_b32 s12, v249, 61
	s_nop 0
	ds_read_b128 v[6:9], v63 offset:18432
	s_waitcnt lgkmcnt(0)
	v_mfma_f32_16x16x32_bf16 v[6:9], v[6:9], v[2:5], 0
	v_readlane_b32 s13, v249, 62
	s_addk_i32 s14, 0x100
	v_readlane_b32 s37, v249, 17
	v_mfma_f32_16x16x32_bf16 v[22:25], v[10:13], v[70:73], v[6:9]
	ds_read_b128 v[10:13], v64 offset:18496
	v_cndmask_b32_e64 v41, v69, v41, s[12:13]
	v_readlane_b32 s12, v249, 63
	s_nop 0
	ds_read_b128 v[6:9], v64 offset:18432
	s_waitcnt lgkmcnt(0)
	v_mfma_f32_16x16x32_bf16 v[6:9], v[6:9], v[2:5], 0
	v_readlane_b32 s13, v248, 0
	v_cndmask_b32_e64 v22, v69, v22, s[30:31]
	v_cndmask_b32_e64 v23, v69, v23, s[34:35]
	v_mfma_f32_16x16x32_bf16 v[18:21], v[10:13], v[70:73], v[6:9]
	ds_read_b128 v[10:13], v65 offset:18496
	v_cndmask_b32_e64 v34, v69, v34, s[12:13]
	v_readlane_b32 s12, v248, 1
	s_nop 0
	ds_read_b128 v[6:9], v65 offset:18432
	s_waitcnt lgkmcnt(0)
	v_mfma_f32_16x16x32_bf16 v[6:9], v[6:9], v[2:5], 0
	v_readlane_b32 s13, v248, 2
	s_waitcnt vmcnt(0)
	v_mov_b32_e32 v44, v114
	v_max3_f32 v47, v44, v38, v39
	v_max3_f32 v47, v47, v40, v41
	v_mfma_f32_16x16x32_bf16 v[14:17], v[10:13], v[70:73], v[6:9]
	ds_read_b128 v[10:13], v66 offset:18496
	v_cndmask_b32_e64 v35, v69, v35, s[12:13]
	v_readlane_b32 s12, v248, 3
	ds_read_b128 v[6:9], v66 offset:18432
	s_waitcnt lgkmcnt(0)
	v_mfma_f32_16x16x32_bf16 v[6:9], v[6:9], v[2:5], 0
	v_readlane_b32 s13, v248, 4
	v_max3_f32 v47, v47, v34, v35
	v_cndmask_b32_e64 v24, v69, v24, s[20:21]
	v_mfma_f32_16x16x32_bf16 v[10:13], v[10:13], v[70:73], v[6:9]
	v_cndmask_b32_e64 v36, v69, v36, s[12:13]
	v_readlane_b32 s12, v248, 5
	v_readlane_b32 s13, v248, 6
	s_nop 0
	ds_read_b128 v[6:9], v67 offset:18432
	s_waitcnt lgkmcnt(0)
	v_mfma_f32_16x16x32_bf16 v[6:9], v[6:9], v[2:5], 0
	v_cndmask_b32_e64 v37, v69, v37, s[12:13]
	v_readlane_b32 s12, v248, 7
	v_readlane_b32 s13, v248, 8
	v_mfma_f32_16x16x32_bf16 v[6:9], v[74:77], v[70:73], v[6:9]
	ds_read_b128 v[74:77], v68 offset:18432
	v_cndmask_b32_e64 v30, v69, v30, s[12:13]
	v_readlane_b32 s12, v248, 9
	v_readlane_b32 s13, v248, 10
	s_waitcnt lgkmcnt(0)
	v_mfma_f32_16x16x32_bf16 v[2:5], v[74:77], v[2:5], 0
	v_cndmask_b32_e64 v31, v69, v31, s[12:13]
	v_readlane_b32 s12, v248, 11
	v_readlane_b32 s13, v248, 12
	ds_read_b128 v[74:77], v68 offset:18496
	v_max3_f32 v47, v47, v36, v37
	v_cndmask_b32_e64 v32, v69, v32, s[12:13]
	v_readlane_b32 s12, v248, 13
	v_readlane_b32 s13, v248, 14
	v_max3_f32 v47, v47, v30, v31
	v_cndmask_b32_e64 v25, v69, v25, s[22:23]
	v_cndmask_b32_e64 v33, v69, v33, s[12:13]
	v_readlane_b32 s12, v248, 15
	v_readlane_b32 s13, v248, 16
	v_max3_f32 v47, v47, v32, v33
	s_waitcnt lgkmcnt(0)
	v_mfma_f32_16x16x32_bf16 v[2:5], v[74:77], v[70:73], v[2:5]
	v_cndmask_b32_e64 v26, v69, v26, s[12:13]
	v_readlane_b32 s12, v248, 17
	v_readlane_b32 s13, v248, 18
	v_cndmask_b32_e64 v70, v69, v18, s[24:25]
	v_cndmask_b32_e64 v71, v69, v19, s[26:27]
	v_cndmask_b32_e64 v27, v69, v27, s[12:13]
	v_readlane_b32 s12, v248, 19
	v_readlane_b32 s13, v248, 20
	v_max3_f32 v47, v47, v26, v27
	v_cndmask_b32_e64 v72, v69, v21, s[54:55]
	v_cndmask_b32_e64 v28, v69, v28, s[12:13]
	v_readlane_b32 s12, v248, 21
	v_readlane_b32 s13, v248, 22
	v_cndmask_b32_e64 v73, v69, v14, s[56:57]
	v_cndmask_b32_e64 v74, v69, v15, s[58:59]
	v_cndmask_b32_e64 v29, v69, v29, s[12:13]
	v_max3_f32 v47, v47, v28, v29
	v_max3_f32 v47, v47, v22, v23
	v_max3_f32 v47, v47, v24, v25
	v_max3_f32 v18, v47, v70, v71
	v_cndmask_b32_e64 v47, v69, v20, s[52:53]
	v_max3_f32 v18, v18, v47, v72
	v_max3_f32 v14, v18, v73, v74
	v_cndmask_b32_e64 v75, v69, v16, s[60:61]
	v_cndmask_b32_e64 v76, v69, v17, s[62:63]
	v_max3_f32 v14, v14, v75, v76
	v_cndmask_b32_e64 v77, v69, v10, s[64:65]
	v_cndmask_b32_e64 v78, v69, v11, s[66:67]
	v_max3_f32 v10, v14, v77, v78
	v_cndmask_b32_e64 v79, v69, v12, s[68:69]
	v_cndmask_b32_e64 v80, v69, v13, s[70:71]
	v_max3_f32 v10, v10, v79, v80
	v_cndmask_b32_e64 v81, v69, v6, s[72:73]
	v_cndmask_b32_e64 v82, v69, v7, s[74:75]
	v_max3_f32 v6, v10, v81, v82
	v_cndmask_b32_e64 v83, v69, v8, s[76:77]
	v_cndmask_b32_e64 v84, v69, v9, s[78:79]
	v_max3_f32 v6, v6, v83, v84
	v_cndmask_b32_e64 v85, v69, v2, s[80:81]
	v_cndmask_b32_e64 v86, v69, v3, s[82:83]
	v_max3_f32 v2, v6, v85, v86
	v_cndmask_b32_e64 v87, v69, v4, s[84:85]
	v_cndmask_b32_e64 v88, v69, v5, s[86:87]
	v_max3_f32 v2, v2, v87, v88
	ds_bpermute_b32 v3, v43, v2
	v_readlane_b32 s40, v249, 20
	v_readlane_b32 s41, v249, 21
	v_readlane_b32 s42, v249, 22
	v_readlane_b32 s43, v249, 23
	s_waitcnt lgkmcnt(0)
	v_max_f32_e32 v3, v3, v3
	v_max_f32_e32 v2, v2, v3
	ds_bpermute_b32 v3, v48, v2
	v_readlane_b32 s44, v249, 24
	v_readlane_b32 s45, v249, 25
	v_readlane_b32 s46, v249, 26
	v_readlane_b32 s47, v249, 27
	s_waitcnt lgkmcnt(0)
	v_max_f32_e32 v3, v3, v3
	v_max_f32_e32 v89, v2, v3
	v_sub_f32_e32 v2, v38, v89
	v_mul_f32_e32 v2, 0x3fb8aa3b, v2
	v_sub_f32_e32 v3, v39, v89
	v_exp_f32_e32 v2, v2
	v_mul_f32_e32 v3, 0x3fb8aa3b, v3
	v_exp_f32_e32 v3, v3
	v_sub_f32_e32 v44, v44, v89
	v_add_f32_e32 v4, 0, v2
	v_mul_f32_e32 v44, 0x3fb8aa3b, v44
	v_add_f32_e32 v5, v3, v4
	v_sub_f32_e32 v4, v40, v89
	v_mul_f32_e32 v4, 0x3fb8aa3b, v4
	v_exp_f32_e32 v4, v4
	v_exp_f32_e32 v44, v44
	v_readlane_b32 s48, v249, 28
	v_readlane_b32 s49, v249, 29
	v_add_f32_e32 v6, v4, v5
	v_sub_f32_e32 v5, v41, v89
	v_mul_f32_e32 v5, 0x3fb8aa3b, v5
	v_exp_f32_e32 v5, v5
	v_readlane_b32 s50, v249, 30
	v_readlane_b32 s51, v249, 31
	v_add_f32_e32 v7, v5, v6
	v_sub_f32_e32 v6, v34, v89
	v_mul_f32_e32 v6, 0x3fb8aa3b, v6
	v_exp_f32_e32 v6, v6
	s_nop 0
	v_add_f32_e32 v8, v6, v7
	v_sub_f32_e32 v7, v35, v89
	v_mul_f32_e32 v7, 0x3fb8aa3b, v7
	v_exp_f32_e32 v7, v7
	s_nop 0
	v_add_f32_e32 v9, v7, v8
	v_sub_f32_e32 v8, v36, v89
	v_mul_f32_e32 v8, 0x3fb8aa3b, v8
	v_exp_f32_e32 v8, v8
	s_nop 0
	v_add_f32_e32 v10, v8, v9
	v_sub_f32_e32 v9, v37, v89
	v_mul_f32_e32 v9, 0x3fb8aa3b, v9
	v_exp_f32_e32 v9, v9
	s_nop 0
	v_add_f32_e32 v11, v9, v10
	v_sub_f32_e32 v10, v30, v89
	v_mul_f32_e32 v10, 0x3fb8aa3b, v10
	v_exp_f32_e32 v10, v10
	s_nop 0
	v_add_f32_e32 v12, v10, v11
	v_sub_f32_e32 v11, v31, v89
	v_mul_f32_e32 v11, 0x3fb8aa3b, v11
	v_exp_f32_e32 v11, v11
	s_nop 0
	v_add_f32_e32 v13, v11, v12
	v_sub_f32_e32 v12, v32, v89
	v_mul_f32_e32 v12, 0x3fb8aa3b, v12
	v_exp_f32_e32 v12, v12
	s_nop 0
	v_add_f32_e32 v14, v12, v13
	v_sub_f32_e32 v13, v33, v89
	v_mul_f32_e32 v13, 0x3fb8aa3b, v13
	v_exp_f32_e32 v13, v13
	s_nop 0
	v_add_f32_e32 v15, v13, v14
	v_sub_f32_e32 v14, v26, v89
	v_mul_f32_e32 v14, 0x3fb8aa3b, v14
	v_exp_f32_e32 v14, v14
	s_nop 0
	v_add_f32_e32 v16, v14, v15
	v_sub_f32_e32 v15, v27, v89
	v_mul_f32_e32 v15, 0x3fb8aa3b, v15
	v_exp_f32_e32 v15, v15
	s_nop 0
	v_add_f32_e32 v17, v15, v16
	v_sub_f32_e32 v16, v28, v89
	v_mul_f32_e32 v16, 0x3fb8aa3b, v16
	v_exp_f32_e32 v16, v16
	s_nop 0
	v_add_f32_e32 v18, v16, v17
	v_sub_f32_e32 v17, v29, v89
	v_mul_f32_e32 v17, 0x3fb8aa3b, v17
	v_exp_f32_e32 v17, v17
	s_nop 0
	v_add_f32_e32 v19, v17, v18
	v_sub_f32_e32 v18, v22, v89
	v_mul_f32_e32 v18, 0x3fb8aa3b, v18
	v_exp_f32_e32 v18, v18
	s_nop 0
	v_add_f32_e32 v20, v18, v19
	v_sub_f32_e32 v19, v23, v89
	v_mul_f32_e32 v19, 0x3fb8aa3b, v19
	v_exp_f32_e32 v19, v19
	s_nop 0
	v_add_f32_e32 v21, v19, v20
	v_sub_f32_e32 v20, v24, v89
	v_mul_f32_e32 v20, 0x3fb8aa3b, v20
	v_exp_f32_e32 v20, v20
	s_nop 0
	v_add_f32_e32 v22, v20, v21
	v_sub_f32_e32 v21, v25, v89
	v_mul_f32_e32 v21, 0x3fb8aa3b, v21
	v_exp_f32_e32 v21, v21
	s_nop 0
	v_add_f32_e32 v23, v21, v22
	v_sub_f32_e32 v22, v70, v89
	v_mul_f32_e32 v22, 0x3fb8aa3b, v22
	v_exp_f32_e32 v22, v22
	s_nop 0
	v_add_f32_e32 v24, v22, v23
	v_sub_f32_e32 v23, v71, v89
	v_mul_f32_e32 v23, 0x3fb8aa3b, v23
	v_exp_f32_e32 v23, v23
	s_nop 0
	v_add_f32_e32 v25, v23, v24
	v_sub_f32_e32 v24, v47, v89
	v_mul_f32_e32 v24, 0x3fb8aa3b, v24
	v_exp_f32_e32 v24, v24
	s_nop 0
	v_add_f32_e32 v26, v24, v25
	v_sub_f32_e32 v25, v72, v89
	v_mul_f32_e32 v25, 0x3fb8aa3b, v25
	v_exp_f32_e32 v25, v25
	s_nop 0
	v_add_f32_e32 v27, v25, v26
	v_sub_f32_e32 v26, v73, v89
	v_mul_f32_e32 v26, 0x3fb8aa3b, v26
	v_exp_f32_e32 v26, v26
	s_nop 0
	v_add_f32_e32 v28, v26, v27
	v_sub_f32_e32 v27, v74, v89
	v_mul_f32_e32 v27, 0x3fb8aa3b, v27
	v_exp_f32_e32 v27, v27
	s_nop 0
	v_add_f32_e32 v29, v27, v28
	v_sub_f32_e32 v28, v75, v89
	v_mul_f32_e32 v28, 0x3fb8aa3b, v28
	v_exp_f32_e32 v28, v28
	s_nop 0
	v_add_f32_e32 v30, v28, v29
	v_sub_f32_e32 v29, v76, v89
	v_mul_f32_e32 v29, 0x3fb8aa3b, v29
	v_exp_f32_e32 v29, v29
	s_nop 0
	v_add_f32_e32 v31, v29, v30
	v_sub_f32_e32 v30, v77, v89
	v_mul_f32_e32 v30, 0x3fb8aa3b, v30
	v_exp_f32_e32 v30, v30
	s_nop 0
	v_add_f32_e32 v32, v30, v31
	v_sub_f32_e32 v31, v78, v89
	v_mul_f32_e32 v31, 0x3fb8aa3b, v31
	v_exp_f32_e32 v31, v31
	s_nop 0
	v_add_f32_e32 v33, v31, v32
	v_sub_f32_e32 v32, v79, v89
	v_mul_f32_e32 v32, 0x3fb8aa3b, v32
	v_exp_f32_e32 v32, v32
	s_nop 0
	v_add_f32_e32 v34, v32, v33
	v_sub_f32_e32 v33, v80, v89
	v_mul_f32_e32 v33, 0x3fb8aa3b, v33
	v_exp_f32_e32 v33, v33
	s_nop 0
	v_add_f32_e32 v35, v33, v34
	v_sub_f32_e32 v34, v81, v89
	v_mul_f32_e32 v34, 0x3fb8aa3b, v34
	v_exp_f32_e32 v34, v34
	s_nop 0
	v_add_f32_e32 v36, v34, v35
	v_sub_f32_e32 v35, v82, v89
	v_mul_f32_e32 v35, 0x3fb8aa3b, v35
	v_exp_f32_e32 v35, v35
	s_nop 0
	v_add_f32_e32 v37, v35, v36
	v_sub_f32_e32 v36, v83, v89
	v_mul_f32_e32 v36, 0x3fb8aa3b, v36
	v_exp_f32_e32 v36, v36
	s_nop 0
	v_add_f32_e32 v38, v36, v37
	v_sub_f32_e32 v37, v84, v89
	v_mul_f32_e32 v37, 0x3fb8aa3b, v37
	v_exp_f32_e32 v37, v37
	s_nop 0
	v_add_f32_e32 v39, v37, v38
	v_sub_f32_e32 v38, v85, v89
	v_mul_f32_e32 v38, 0x3fb8aa3b, v38
	v_exp_f32_e32 v38, v38
	s_nop 0
	v_add_f32_e32 v40, v38, v39
	v_sub_f32_e32 v39, v86, v89
	v_mul_f32_e32 v39, 0x3fb8aa3b, v39
	v_exp_f32_e32 v39, v39
	s_nop 0
	v_add_f32_e32 v41, v39, v40
	v_sub_f32_e32 v40, v87, v89
	v_mul_f32_e32 v40, 0x3fb8aa3b, v40
	v_exp_f32_e32 v40, v40
	s_nop 0
	v_add_f32_e32 v47, v40, v41
	v_sub_f32_e32 v41, v88, v89
	v_mul_f32_e32 v41, 0x3fb8aa3b, v41
	v_exp_f32_e32 v41, v41
	s_nop 0
	v_add_f32_e32 v47, v41, v47
	ds_bpermute_b32 v70, v43, v47
	s_waitcnt lgkmcnt(0)
	v_add_f32_e32 v47, v47, v70
	ds_bpermute_b32 v70, v48, v47
	s_waitcnt lgkmcnt(0)
	v_add_f32_e32 v47, v47, v70
	v_add_f32_e32 v44, v44, v47
	v_div_scale_f32 v47, s[12:13], v44, v44, 1.0
	v_rcp_f32_e32 v70, v47
	s_nop 0
	v_fma_f32 v71, -v47, v70, 1.0
	v_fmac_f32_e32 v70, v71, v70
	v_div_scale_f32 v71, vcc, 1.0, v44, 1.0
	v_mul_f32_e32 v72, v71, v70
	v_fma_f32 v73, -v47, v72, v71
	v_fmac_f32_e32 v72, v73, v70
	v_fma_f32 v47, -v47, v72, v71
	v_div_fmas_f32 v47, v47, v70, v72
	v_div_fixup_f32 v44, v47, v44, 1.0
	v_pk_mul_f32 v[2:3], v[2:3], v[44:45] op_sel_hi:[1,0]
	v_pk_mul_f32 v[4:5], v[4:5], v[44:45] op_sel_hi:[1,0]
	v_cvt_pk_bf16_f32 v2, v2, v3
	v_cvt_pk_bf16_f32 v3, v4, v5
	v_pk_mul_f32 v[4:5], v[6:7], v[44:45] op_sel_hi:[1,0]
	v_pk_mul_f32 v[6:7], v[8:9], v[44:45] op_sel_hi:[1,0]
	v_cvt_pk_bf16_f32 v4, v4, v5
	v_cvt_pk_bf16_f32 v5, v6, v7
	ds_write2_b64 v51, v[2:3], v[4:5] offset1:4
	v_pk_mul_f32 v[2:3], v[10:11], v[44:45] op_sel_hi:[1,0]
	v_pk_mul_f32 v[4:5], v[12:13], v[44:45] op_sel_hi:[1,0]
	v_cvt_pk_bf16_f32 v2, v2, v3
	v_cvt_pk_bf16_f32 v3, v4, v5
	v_pk_mul_f32 v[4:5], v[14:15], v[44:45] op_sel_hi:[1,0]
	v_pk_mul_f32 v[6:7], v[16:17], v[44:45] op_sel_hi:[1,0]
	v_cvt_pk_bf16_f32 v4, v4, v5
	v_cvt_pk_bf16_f32 v5, v6, v7
	ds_write2_b64 v51, v[2:3], v[4:5] offset0:8 offset1:12
	v_pk_mul_f32 v[2:3], v[18:19], v[44:45] op_sel_hi:[1,0]
	v_pk_mul_f32 v[4:5], v[20:21], v[44:45] op_sel_hi:[1,0]
	v_cvt_pk_bf16_f32 v2, v2, v3
	v_cvt_pk_bf16_f32 v3, v4, v5
	v_pk_mul_f32 v[4:5], v[22:23], v[44:45] op_sel_hi:[1,0]
	v_pk_mul_f32 v[6:7], v[24:25], v[44:45] op_sel_hi:[1,0]
	v_cvt_pk_bf16_f32 v4, v4, v5
	v_cvt_pk_bf16_f32 v5, v6, v7
	ds_write2_b64 v51, v[2:3], v[4:5] offset0:16 offset1:20
	v_pk_mul_f32 v[2:3], v[26:27], v[44:45] op_sel_hi:[1,0]
	v_pk_mul_f32 v[4:5], v[28:29], v[44:45] op_sel_hi:[1,0]
	v_cvt_pk_bf16_f32 v2, v2, v3
	v_cvt_pk_bf16_f32 v3, v4, v5
	v_pk_mul_f32 v[4:5], v[30:31], v[44:45] op_sel_hi:[1,0]
	v_pk_mul_f32 v[6:7], v[32:33], v[44:45] op_sel_hi:[1,0]
	v_cvt_pk_bf16_f32 v4, v4, v5
	v_cvt_pk_bf16_f32 v5, v6, v7
	ds_write2_b64 v51, v[2:3], v[4:5] offset0:24 offset1:28
	v_pk_mul_f32 v[2:3], v[34:35], v[44:45] op_sel_hi:[1,0]
	v_pk_mul_f32 v[4:5], v[36:37], v[44:45] op_sel_hi:[1,0]
	v_cvt_pk_bf16_f32 v2, v2, v3
	v_cvt_pk_bf16_f32 v3, v4, v5
	v_pk_mul_f32 v[4:5], v[38:39], v[44:45] op_sel_hi:[1,0]
	v_pk_mul_f32 v[6:7], v[40:41], v[44:45] op_sel_hi:[1,0]
	v_cvt_pk_bf16_f32 v4, v4, v5
	v_cvt_pk_bf16_f32 v5, v6, v7
	ds_write2_b64 v51, v[2:3], v[4:5] offset0:32 offset1:36
	s_waitcnt lgkmcnt(0)
	ds_read_b128 v[2:5], v52
	ds_read_b64_tr_b16 v[8:9], v53 offset:58176
	ds_read_b64_tr_b16 v[6:7], v53 offset:57600
	ds_read_b64_tr_b16 v[10:11], v53 offset:57632
	ds_read_b64_tr_b16 v[12:13], v53 offset:58208
	ds_read_b64_tr_b16 v[14:15], v53 offset:57664
	ds_read_b64_tr_b16 v[16:17], v53 offset:58240
	ds_read_b64_tr_b16 v[18:19], v53 offset:57696
	ds_read_b64_tr_b16 v[20:21], v53 offset:58272
	s_waitcnt lgkmcnt(6)
	v_mfma_f32_16x16x32_bf16 v[6:9], v[6:9], v[2:5], 0
	v_mov_b32_e32 v47, v45
	s_waitcnt lgkmcnt(4)
	v_mfma_f32_16x16x32_bf16 v[10:13], v[10:13], v[2:5], 0
	s_waitcnt lgkmcnt(2)
	v_mfma_f32_16x16x32_bf16 v[14:17], v[14:17], v[2:5], 0
	s_waitcnt lgkmcnt(0)
	v_mfma_f32_16x16x32_bf16 v[2:5], v[18:21], v[2:5], 0
	ds_read_b128 v[18:21], v52 offset:64
	ds_read_b64_tr_b16 v[22:23], v53 offset:62208
	ds_read_b64_tr_b16 v[24:25], v53 offset:62784
	s_waitcnt lgkmcnt(0)
	v_mfma_f32_16x16x32_bf16 v[6:9], v[22:25], v[18:21], v[6:9]
	ds_read_b64_tr_b16 v[22:23], v53 offset:62240
	ds_read_b64_tr_b16 v[24:25], v53 offset:62816
	s_waitcnt lgkmcnt(0)
	v_mfma_f32_16x16x32_bf16 v[10:13], v[22:25], v[18:21], v[10:13]
	ds_read_b64_tr_b16 v[22:23], v53 offset:62272
	ds_read_b64_tr_b16 v[24:25], v53 offset:62848
	s_waitcnt lgkmcnt(0)
	v_mfma_f32_16x16x32_bf16 v[14:17], v[22:25], v[18:21], v[14:17]
	ds_read_b64_tr_b16 v[22:23], v53 offset:62304
	ds_read_b64_tr_b16 v[24:25], v53 offset:62880
	s_waitcnt lgkmcnt(0)
	v_mfma_f32_16x16x32_bf16 v[2:5], v[22:25], v[18:21], v[2:5]
	ds_read_b128 v[18:21], v52 offset:128
	ds_read_b64_tr_b16 v[24:25], v54 offset:9792
	ds_read_b64_tr_b16 v[22:23], v54 offset:9216
	ds_read_b64_tr_b16 v[26:27], v54 offset:9248
	ds_read_b64_tr_b16 v[28:29], v54 offset:9824
	s_waitcnt lgkmcnt(2)
	v_mfma_f32_16x16x32_bf16 v[6:9], v[22:25], v[18:21], v[6:9]
	ds_read_b64_tr_b16 v[22:23], v54 offset:9280
	ds_read_b64_tr_b16 v[24:25], v54 offset:9856
	s_waitcnt lgkmcnt(0)
	v_mfma_f32_16x16x32_bf16 v[14:17], v[22:25], v[18:21], v[14:17]
	ds_read_b64_tr_b16 v[22:23], v54 offset:9312
	ds_read_b64_tr_b16 v[24:25], v54 offset:9888
	v_mfma_f32_16x16x32_bf16 v[10:13], v[26:29], v[18:21], v[10:13]
	v_add_u32_e32 v28, s16, v49
	v_lshlrev_b32_e32 v29, 6, v28
	v_and_b32_e32 v30, 0x3c0, v29
	s_waitcnt lgkmcnt(0)
	v_mfma_f32_16x16x32_bf16 v[2:5], v[22:25], v[18:21], v[2:5]
	ds_read_b128 v[18:21], v52 offset:192
	ds_read_b64_tr_b16 v[22:23], v54 offset:13824
	ds_read_b64_tr_b16 v[24:25], v54 offset:14400
	s_waitcnt lgkmcnt(0)
	v_mfma_f32_16x16x32_bf16 v[6:9], v[22:25], v[18:21], v[6:9]
	ds_read_b64_tr_b16 v[22:23], v54 offset:13856
	ds_read_b64_tr_b16 v[24:25], v54 offset:14432
	s_waitcnt lgkmcnt(0)
	v_mfma_f32_16x16x32_bf16 v[10:13], v[22:25], v[18:21], v[10:13]
	ds_read_b64_tr_b16 v[22:23], v54 offset:13888
	ds_read_b64_tr_b16 v[24:25], v54 offset:14464
	s_waitcnt lgkmcnt(0)
	v_mfma_f32_16x16x32_bf16 v[22:25], v[22:25], v[18:21], v[14:17]
	s_nop 2
	ds_read_b64_tr_b16 v[14:15], v54 offset:13920
	ds_read_b64_tr_b16 v[16:17], v54 offset:14496
	s_waitcnt lgkmcnt(0)
	v_mfma_f32_16x16x32_bf16 v[2:5], v[14:17], v[18:21], v[2:5]
	ds_read_b128 v[18:21], v52 offset:256
	ds_read_b64_tr_b16 v[14:15], v54 offset:18432
	ds_read_b64_tr_b16 v[16:17], v54 offset:19008
	s_waitcnt lgkmcnt(0)
	v_mfma_f32_16x16x32_bf16 v[14:17], v[14:17], v[18:21], v[6:9]
	s_nop 2
	ds_read_b64_tr_b16 v[6:7], v54 offset:18464
	ds_read_b64_tr_b16 v[8:9], v54 offset:19040
	s_waitcnt lgkmcnt(0)
	v_mfma_f32_16x16x32_bf16 v[10:13], v[6:9], v[18:21], v[10:13]
	ds_read_b64_tr_b16 v[6:7], v54 offset:18496
	ds_read_b64_tr_b16 v[8:9], v54 offset:19072
	s_waitcnt lgkmcnt(0)
	v_mfma_f32_16x16x32_bf16 v[6:9], v[6:9], v[18:21], v[22:25]
	s_nop 2
	ds_read_b64_tr_b16 v[22:23], v54 offset:18528
	ds_read_b64_tr_b16 v[24:25], v54 offset:19104
	s_waitcnt lgkmcnt(0)
	v_mfma_f32_16x16x32_bf16 v[2:5], v[22:25], v[18:21], v[2:5]
	v_mov_b64_e32 v[18:19], s[96:97]
	v_mad_i64_i32 v[18:19], s[12:13], v28, s33, v[18:19]
	s_lshl_b32 s12, s10, 7
	s_mov_b32 s13, s3
	v_lshl_add_u64 v[18:19], v[18:19], 0, s[12:13]
	v_lshl_add_u64 v[18:19], v[18:19], 0, v[46:47]
	s_mov_b64 s[12:13], 0x3200
	v_lshl_add_u64 v[24:25], v[18:19], 0, s[12:13]
	v_add_co_u32_e32 v18, vcc, s11, v18
	s_add_i32 s10, s10, 32
	s_nop 0
	v_addc_co_u32_e32 v19, vcc, 0, v19, vcc
	v_mov_b32_e32 v26, v106
	v_mov_b32_e32 v27, v107
	v_mov_b32_e32 v22, v108
	v_mov_b32_e32 v23, v109
	v_mov_b32_e32 v20, v110
	v_mov_b32_e32 v21, v111
	v_mov_b32_e32 v18, v112
	v_mov_b32_e32 v19, v113
	v_ashrrev_i32_e32 v24, 7, v28
	v_ashrrev_i32_e32 v25, 31, v24
	v_lshlrev_b64 v[24:25], 20, v[24:25]
	v_lshlrev_b32_e32 v28, 2, v28
	s_waitcnt vmcnt(3)
	v_and_b32_e32 v31, 32, v28
	v_lshl_add_u64 v[28:29], s[6:7], 0, v[24:25]
	v_lshlrev_b32_e32 v24, 16, v26
	v_and_b32_e32 v25, 0xffff0000, v26
	v_pk_mul_f32 v[14:15], v[14:15], v[24:25]
	s_mov_b32 s11, s3
	v_cvt_pk_bf16_f32 v24, v14, v15
	v_lshlrev_b32_e32 v14, 16, v27
	v_and_b32_e32 v15, 0xffff0000, v27
	v_pk_mul_f32 v[14:15], v[16:17], v[14:15]
	s_lshl_b64 s[10:11], s[10:11], 14
	v_cvt_pk_bf16_f32 v25, v14, v15
	v_or3_b32 v44, v30, v55, v31
	v_lshl_add_u64 v[14:15], v[28:29], 0, s[10:11]
	s_waitcnt vmcnt(2)
	v_lshl_add_u64 v[16:17], v[14:15], 0, v[44:45]
	s_waitcnt vmcnt(1)
	s_waitcnt vmcnt(0)
	global_store_dwordx2 v[16:17], v[24:25], off
	v_lshlrev_b32_e32 v24, 16, v22
	v_and_b32_e32 v25, 0xffff0000, v22
	v_lshlrev_b32_e32 v22, 16, v23
	v_and_b32_e32 v23, 0xffff0000, v23
	v_pk_mul_f32 v[12:13], v[12:13], v[22:23]
	v_or_b32_e32 v22, v30, v56
	v_pk_mul_f32 v[10:11], v[10:11], v[24:25]
	v_bitop3_b32 v44, v31, s9, v22 bitop3:0xde
	v_cvt_pk_bf16_f32 v10, v10, v11
	v_cvt_pk_bf16_f32 v11, v12, v13
	v_lshl_add_u64 v[12:13], v[14:15], 0, v[44:45]
	global_store_dwordx2 v[12:13], v[10:11], off
	v_lshlrev_b32_e32 v10, 16, v20
	v_and_b32_e32 v11, 0xffff0000, v20
	v_pk_mul_f32 v[6:7], v[6:7], v[10:11]
	v_lshlrev_b32_e32 v10, 16, v21
	v_and_b32_e32 v11, 0xffff0000, v21
	v_pk_mul_f32 v[8:9], v[8:9], v[10:11]
	v_cvt_pk_bf16_f32 v6, v6, v7
	v_cvt_pk_bf16_f32 v7, v8, v9
	global_store_dwordx2 v[16:17], v[6:7], off offset:1024
	v_lshlrev_b32_e32 v6, 16, v18
	v_and_b32_e32 v7, 0xffff0000, v18
	v_pk_mul_f32 v[2:3], v[2:3], v[6:7]
	v_lshlrev_b32_e32 v6, 16, v19
	v_and_b32_e32 v7, 0xffff0000, v19
	v_pk_mul_f32 v[4:5], v[4:5], v[6:7]
	v_xad_u32 v44, v31, v22, s9
	v_cvt_pk_bf16_f32 v2, v2, v3
	v_cvt_pk_bf16_f32 v3, v4, v5
	v_lshl_add_u64 v[4:5], v[14:15], 0, v[44:45]
	s_cmp_eq_u32 s15, 4
	global_store_dwordx2 v[4:5], v[2:3], off offset:1024
	s_cbranch_scc1 .LBB0_1435
.LBB0_1424:
	s_lshl_b32 s11, s15, 8
	s_add_i32 s11, s11, s17
	s_and_b32 s11, s11, 0xfffff000
	s_or_b32 s10, s29, s15
	s_or_b32 s16, s11, s28
	v_lshlrev_b32_e32 v44, 1, v42
	v_add_u32_e32 v100, s16, v49
	v_mov_b64_e32 v[102:103], s[96:97]
	v_mad_i64_i32 v[102:103], s[12:13], v100, s33, v[102:103]
	s_lshl_b32 s12, s10, 7
	s_mov_b32 s13, s3
	v_lshl_add_u64 v[102:103], v[102:103], 0, s[12:13]
	v_mov_b32_e32 v104, v46
	v_mov_b32_e32 v105, 0
	v_lshl_add_u64 v[102:103], v[102:103], 0, v[104:105]
	s_mov_b64 s[12:13], 0x3200
	v_lshl_add_u64 v[102:103], v[102:103], 0, s[12:13]
	global_load_dwordx2 v[106:107], v[102:103], off
	global_load_dwordx2 v[108:109], v[102:103], off offset:32
	global_load_dwordx2 v[110:111], v[102:103], off offset:64
	global_load_dwordx2 v[112:113], v[102:103], off offset:96
	v_readlane_b32 s12, v249, 18
	v_readlane_b32 s13, v249, 19
	v_lshlrev_b32_e64 v101, 2, s10
	s_nop 4
	global_load_dword v114, v101, s[12:13] offset:64
	s_barrier
	s_mov_b64 s[90:91], exec
	v_readlane_b32 s12, v249, 0
	v_readlane_b32 s13, v249, 1
	s_and_b64 s[12:13], s[90:91], s[12:13]
	s_mov_b64 exec, s[12:13]
	s_cbranch_execz .LBB0_1428
	v_or_b32_e32 v12, s16, v1
	v_mov_b64_e32 v[2:3], s[96:97]
	v_mad_i64_i32 v[2:3], s[12:13], v12, s33, v[2:3]
	s_lshl_b32 s12, s10, 7
	s_mov_b32 s13, s3
	v_lshl_add_u64 v[2:3], v[2:3], 0, s[12:13]
	v_lshl_add_u64 v[2:3], v[2:3], 0, v[44:45]
	v_add_co_u32_e32 v4, vcc, 0x2000, v2
	s_mov_b64 s[12:13], 0x2800
	s_nop 0
	v_addc_co_u32_e32 v5, vcc, 0, v3, vcc
	v_lshl_add_u64 v[2:3], v[2:3], 0, s[12:13]
	global_load_dwordx4 v[8:11], v[4:5], off offset:2048
	global_load_dwordx4 v[14:17], v[2:3], off offset:16
	s_and_saveexec_b64 s[12:13], s[88:89]
	v_mov_b32_e32 v116, v12
	v_ashrrev_i32_e32 v117, 31, v12
	v_lshlrev_b64 v[116:117], 6, v[116:117]
	v_lshl_add_u64 v[116:117], s[4:5], 0, v[116:117]
	global_load_dwordx4 v[120:123], v[116:117], off offset:48
	global_load_dwordx4 v[124:127], v[116:117], off offset:32
	global_load_dwordx4 v[128:131], v[116:117], off offset:16
	global_load_dwordx4 v[132:135], v[116:117], off
	s_mov_b64 exec, s[12:13]
	s_waitcnt vmcnt(5)
	v_lshlrev_b32_e32 v2, 16, v11
	v_lshlrev_b32_e32 v20, 16, v8
	v_and_b32_e32 v21, 0xffff0000, v8
	s_waitcnt vmcnt(4)
	v_lshlrev_b32_e32 v4, 16, v14
	v_and_b32_e32 v5, 0xffff0000, v14
	v_lshlrev_b32_e32 v24, 16, v9
	v_and_b32_e32 v25, 0xffff0000, v9
	v_lshlrev_b32_e32 v6, 16, v15
	v_and_b32_e32 v7, 0xffff0000, v15
	v_lshlrev_b32_e32 v22, 16, v10
	v_and_b32_e32 v23, 0xffff0000, v10
	v_lshlrev_b32_e32 v8, 16, v16
	v_and_b32_e32 v9, 0xffff0000, v16
	v_lshlrev_b32_e32 v14, 16, v17
	v_and_b32_e32 v11, 0xffff0000, v11
	v_and_b32_e32 v10, 0xffff0000, v17
	s_and_saveexec_b64 s[12:13], s[88:89]
	s_cbranch_execz .LBB0_1427
	v_ashrrev_i32_e32 v13, 31, v12
	v_lshlrev_b64 v[12:13], 6, v[12:13]
	v_lshl_add_u64 v[12:13], s[4:5], 0, v[12:13]
	s_waitcnt vmcnt(0)
	v_mov_b32_e32 v26, v120
	v_mov_b32_e32 v27, v121
	v_mov_b32_e32 v28, v122
	v_mov_b32_e32 v29, v123
	v_mov_b32_e32 v30, v124
	v_mov_b32_e32 v31, v125
	v_mov_b32_e32 v32, v126
	v_mov_b32_e32 v33, v127
	v_mov_b32_e32 v16, v128
	v_mov_b32_e32 v17, v129
	v_mov_b32_e32 v18, v130
	v_mov_b32_e32 v19, v131
	v_mov_b32_e32 v34, v132
	v_mov_b32_e32 v35, v133
	v_mov_b32_e32 v36, v134
	v_mov_b32_e32 v37, v135
	v_mov_b32_e32 v3, v11
	v_mov_b32_e32 v15, v10
	s_waitcnt vmcnt(3)
	v_pk_mul_f32 v[10:11], v[28:29], v[10:11]
	s_waitcnt vmcnt(0)
	v_mov_b32_e32 v39, v36
	v_mov_b32_e32 v36, v35
	v_mov_b32_e32 v38, v34
	v_pk_mul_f32 v[12:13], v[36:37], v[4:5]
	s_nop 0
	v_pk_fma_f32 v[12:13], v[38:39], v[20:21], v[12:13] neg_lo:[0,0,1] neg_hi:[0,0,1]
	v_pk_mul_f32 v[20:21], v[36:37], v[20:21]
	s_nop 0
	v_pk_fma_f32 v[4:5], v[38:39], v[4:5], v[20:21]
	v_mov_b32_e32 v21, v18
	v_mov_b32_e32 v18, v17
	v_mov_b32_e32 v20, v16
	v_pk_mul_f32 v[16:17], v[18:19], v[6:7]
	v_pk_mul_f32 v[18:19], v[18:19], v[24:25]
	v_pk_fma_f32 v[16:17], v[20:21], v[24:25], v[16:17] neg_lo:[0,0,1] neg_hi:[0,0,1]
	v_pk_fma_f32 v[6:7], v[20:21], v[6:7], v[18:19]
	v_mov_b32_e32 v21, v32
	v_mov_b32_e32 v32, v31
	v_mov_b32_e32 v20, v30
	v_pk_mul_f32 v[18:19], v[32:33], v[8:9]
	v_mov_b32_e32 v24, v26
	v_pk_fma_f32 v[18:19], v[20:21], v[22:23], v[18:19] neg_lo:[0,0,1] neg_hi:[0,0,1]
	v_pk_mul_f32 v[22:23], v[32:33], v[22:23]
	v_mov_b32_e32 v25, v28
	v_pk_fma_f32 v[8:9], v[20:21], v[8:9], v[22:23]
	v_mul_f32_e32 v20, v26, v14
	v_mul_f32_e32 v22, v27, v2
	v_mov_b32_e32 v26, v27
	v_mov_b32_e32 v27, v29
	v_pk_mul_f32 v[14:15], v[26:27], v[14:15]
	v_mov_b32_e32 v21, v10
	v_mov_b32_e32 v23, v11
	v_pk_fma_f32 v[2:3], v[24:25], v[2:3], v[14:15] neg_lo:[0,0,1] neg_hi:[0,0,1]
	v_pk_add_f32 v[14:15], v[20:21], v[22:23]
	v_mov_b32_e32 v20, v12
	v_mov_b32_e32 v21, v13
	v_mov_b32_e32 v24, v16
	v_mov_b32_e32 v25, v17
	v_mov_b32_e32 v22, v18
	v_mov_b32_e32 v23, v19
	v_mov_b32_e32 v11, v3
	v_mov_b32_e32 v10, v15
